# EpiRes GEMM epilogue: the 16 in-place residual reads prefetched 8 segments ahead with counted vmcnt (global stores)
# speedup vs baseline: 1.0664x; 1.0147x over previous
.LBB0_481:
	v_lshl_add_u32 v172, s76, 8, v194
	v_ashrrev_i32_e32 v173, 31, v172
	v_lshlrev_b64 v[144:145], 12, v[172:173]
	v_cndmask_b32_e64 v146, 0, 1, s[20:21]
	v_cmp_ne_u32_e64 s[6:7], 1, v146
	s_andn2_b64 vcc, exec, s[20:21]
	v_lshl_add_u64 v[178:179], s[48:49], 0, v[144:145]
	v_cmp_gt_i32_e64 s[8:9], s70, v172
	v_subrev_u32_e32 v152, s70, v172
	s_cbranch_vccnz .LBB0_483
	v_lshlrev_b64 v[144:145], 12, v[152:153]
	v_lshl_add_u64 v[144:145], s[28:29], 0, v[144:145]
	v_cndmask_b32_e64 v145, v145, v179, s[8:9]
	v_cndmask_b32_e64 v144, v144, v178, s[8:9]
	v_lshl_add_u64 v[148:149], v[170:171], 2, v[144:145]
	global_load_dwordx4 v[144:147], v[148:149], off offset:16
	s_nop 0
	global_load_dwordx4 v[148:151], v[148:149], off
	s_waitcnt vmcnt(0)
	s_mov_b64 s[8:9], 0
	s_branch .LBB0_484

.LBB0_484:
	v_lshlrev_b64 v[174:175], 11, v[172:173]
	v_lshl_add_u64 v[174:175], s[44:45], 0, v[174:175]
	s_andn2_b64 vcc, exec, s[8:9]
	v_lshl_add_u64 v[176:177], v[170:171], 1, v[174:175]
	s_cbranch_vccnz .LBB0_486
	v_lshlrev_b32_e32 v250, 11, v172
	v_lshl_add_u32 v250, v170, 1, v250
	global_load_dwordx4 v[198:201], v250, s[44:45]
	v_add_u32_e32 v251, 0x100, v250
	global_load_dwordx4 v[202:205], v251, s[44:45]
	v_add_u32_e32 v251, 0x8000, v250
	global_load_dwordx4 v[206:209], v251, s[44:45]
	v_add_u32_e32 v251, 0x8100, v250
	global_load_dwordx4 v[210:213], v251, s[44:45]
	v_add_u32_e32 v251, 0x10000, v250
	global_load_dwordx4 v[214:217], v251, s[44:45]
	v_add_u32_e32 v251, 0x10100, v250
	global_load_dwordx4 v[218:221], v251, s[44:45]
	v_add_u32_e32 v251, 0x18000, v250
	global_load_dwordx4 v[222:225], v251, s[44:45]
	v_add_u32_e32 v251, 0x18100, v250
	global_load_dwordx4 v[238:241], v251, s[44:45]
	s_waitcnt vmcnt(7) lgkmcnt(0)
	v_mov_b32_e32 v144, v198
	v_mov_b32_e32 v145, v199
	v_mov_b32_e32 v146, v200
	v_mov_b32_e32 v147, v201
	v_add_u32_e32 v251, 0x40000, v250
	global_load_dwordx4 v[198:201], v251, s[44:45]
	v_lshlrev_b32_e32 v148, 16, v144
	v_and_b32_e32 v149, 0xffff0000, v144
	v_lshlrev_b32_e32 v150, 16, v145
	v_and_b32_e32 v151, 0xffff0000, v145
	v_lshlrev_b32_e32 v144, 16, v146
	v_and_b32_e32 v145, 0xffff0000, v146
	v_lshlrev_b32_e32 v146, 16, v147
	v_and_b32_e32 v147, 0xffff0000, v147
.LBB0_486:
	v_pk_add_f32 v[142:143], v[142:143], v[70:71]
	v_pk_add_f32 v[140:141], v[140:141], v[68:69]
	v_pk_add_f32 v[138:139], v[138:139], v[66:67]
	v_pk_add_f32 v[136:137], v[136:137], v[64:65]
	v_pk_add_f32 v[150:151], v[142:143], v[150:151]
	v_pk_add_f32 v[148:149], v[140:141], v[148:149]
	v_pk_add_f32 v[146:147], v[138:139], v[146:147]
	v_pk_add_f32 v[180:181], v[136:137], v[144:145]
	v_or_b32_e32 v144, 0x80, v170
	v_cvt_pk_bf16_f32 v136, v148, v149
	v_cvt_pk_bf16_f32 v137, v150, v151
	v_cvt_pk_bf16_f32 v138, v180, v181
	v_cvt_pk_bf16_f32 v139, v146, v147
	s_and_b64 vcc, exec, s[6:7]
	v_ashrrev_i32_e32 v145, 31, v144
	global_store_dwordx4 v[176:177], v[136:139], off
	s_cbranch_vccnz .LBB0_493
	s_nop 0
	v_lshlrev_b64 v[136:137], 12, v[152:153]
	v_lshl_add_u64 v[136:137], s[28:29], 0, v[136:137]
	v_cmp_gt_i32_e32 vcc, s70, v172
	s_nop 1
	v_cndmask_b32_e32 v137, v137, v179, vcc
	v_cndmask_b32_e32 v136, v136, v178, vcc
	v_lshl_add_u64 v[140:141], v[170:171], 2, v[136:137]
	global_load_dwordx4 v[136:139], v[140:141], off offset:528
	s_nop 0
	global_load_dwordx4 v[140:143], v[140:141], off offset:512
	s_waitcnt vmcnt(0)
	s_cbranch_execnz .LBB0_489
.LBB0_488:
	s_waitcnt vmcnt(6) lgkmcnt(0)
	v_mov_b32_e32 v136, v202
	v_mov_b32_e32 v137, v203
	v_mov_b32_e32 v138, v204
	v_mov_b32_e32 v139, v205
	v_add_u32_e32 v251, 0x40100, v250
	global_load_dwordx4 v[202:205], v251, s[44:45]
	v_lshlrev_b32_e32 v140, 16, v136
	v_and_b32_e32 v141, 0xffff0000, v136
	v_lshlrev_b32_e32 v142, 16, v137
	v_and_b32_e32 v143, 0xffff0000, v137
	v_lshlrev_b32_e32 v136, 16, v138
	v_and_b32_e32 v137, 0xffff0000, v138
	v_lshlrev_b32_e32 v138, 16, v139
	v_and_b32_e32 v139, 0xffff0000, v139
.LBB0_489:
	v_mul_f32_e32 v149, v149, v149
	v_fmac_f32_e32 v149, v148, v148
	v_mul_f32_e32 v148, v151, v151
	v_pk_add_f32 v[134:135], v[134:135], v[62:63]
	v_pk_add_f32 v[132:133], v[132:133], v[60:61]
	v_fmac_f32_e32 v148, v150, v150
	v_pk_add_f32 v[134:135], v[134:135], v[142:143]
	v_pk_add_f32 v[132:133], v[132:133], v[140:141]
	v_pk_add_f32 v[128:129], v[128:129], v[56:57]
	v_add_f32_e32 v148, v149, v148
	v_mul_f32_e32 v149, v181, v181
	v_pk_add_f32 v[136:137], v[128:129], v[136:137]
	v_mul_f32_e32 v128, v133, v133
	v_mul_f32_e32 v129, v135, v135
	v_fmac_f32_e32 v149, v180, v180
	v_mul_f32_e32 v147, v147, v147
	v_fmac_f32_e32 v128, v132, v132
	v_fmac_f32_e32 v129, v134, v134
	v_add_f32_e32 v148, v149, v148
	v_fmac_f32_e32 v147, v146, v146
	v_pk_add_f32 v[130:131], v[130:131], v[58:59]
	v_add_f32_e32 v128, v128, v129
	v_mul_f32_e32 v129, v137, v137
	v_add_f32_e32 v146, v147, v148
	v_and_b32_e32 v148, 64, v188
	v_pk_add_f32 v[138:139], v[130:131], v[138:139]
	v_fmac_f32_e32 v129, v136, v136
	v_xor_b32_e32 v147, 16, v188
	v_add_u32_e32 v148, 64, v148
	v_add_f32_e32 v128, v129, v128
	v_mul_f32_e32 v129, v139, v139
	v_cmp_lt_i32_e32 vcc, v147, v148
	v_fmac_f32_e32 v129, v138, v138
	v_add_f32_e32 v128, v129, v128
	v_cndmask_b32_e32 v147, v188, v147, vcc
	v_lshlrev_b32_e32 v149, 2, v147
	v_add_f32_e32 v128, v146, v128
	ds_bpermute_b32 v129, v149, v128
	v_xor_b32_e32 v147, 32, v188
	v_cmp_lt_i32_e32 vcc, v147, v148
	s_lshl_b32 s52, s0, 2
	s_ashr_i32 s53, s52, 31
	v_cndmask_b32_e32 v147, v188, v147, vcc
	v_lshlrev_b32_e32 v150, 2, v147
	s_waitcnt lgkmcnt(0)
	v_add_f32_e32 v128, v128, v129
	ds_bpermute_b32 v129, v150, v128
	v_cvt_pk_bf16_f32 v130, v132, v133
	v_cvt_pk_bf16_f32 v131, v134, v135
	v_cvt_pk_bf16_f32 v132, v136, v137
	v_cvt_pk_bf16_f32 v133, v138, v139
	v_lshl_add_u64 v[134:135], v[144:145], 1, v[174:175]
	global_store_dwordx4 v[134:135], v[130:133], off
	s_and_saveexec_b64 s[8:9], s[10:11]
	s_cbranch_execz .LBB0_491
	v_lshlrev_b64 v[130:131], 6, v[172:173]
	v_lshl_add_u64 v[130:131], s[40:41], 0, v[130:131]
	v_lshl_add_u64 v[130:131], s[52:53], 2, v[130:131]
	s_lshl_b32 s0, s68, 2
	v_lshl_add_u64 v[130:131], v[130:131], 0, s[0:1]
	s_waitcnt lgkmcnt(0)
	v_add_f32_e32 v128, v128, v129
	global_store_dword v[130:131], v128, off
.LBB0_491:
	s_or_b64 exec, exec, s[8:9]
	v_or_b32_e32 v136, 16, v172
	v_ashrrev_i32_e32 v137, 31, v136
	s_waitcnt lgkmcnt(0)
	v_lshlrev_b64 v[128:129], 12, v[136:137]
	s_and_b64 vcc, exec, s[6:7]
	v_lshl_add_u64 v[138:139], s[48:49], 0, v[128:129]
	v_cmp_gt_i32_e64 s[8:9], s70, v136
	v_subrev_u32_e32 v152, s70, v136
	s_cbranch_vccnz .LBB0_494
	v_lshlrev_b64 v[128:129], 12, v[152:153]
	v_lshl_add_u64 v[128:129], s[28:29], 0, v[128:129]
	v_cndmask_b32_e64 v129, v129, v139, s[8:9]
	v_cndmask_b32_e64 v128, v128, v138, s[8:9]
	v_lshl_add_u64 v[132:133], v[170:171], 2, v[128:129]
	global_load_dwordx4 v[128:131], v[132:133], off offset:16
	s_nop 0
	global_load_dwordx4 v[132:135], v[132:133], off
	s_waitcnt vmcnt(0)
	s_mov_b64 s[8:9], 0
	s_branch .LBB0_495

.LBB0_495:
	v_lshlrev_b64 v[140:141], 11, v[136:137]
	v_lshl_add_u64 v[140:141], s[44:45], 0, v[140:141]
	s_andn2_b64 vcc, exec, s[8:9]
	v_lshl_add_u64 v[146:147], v[170:171], 1, v[140:141]
	s_cbranch_vccnz .LBB0_497
	s_waitcnt vmcnt(8) lgkmcnt(0)
	v_mov_b32_e32 v128, v206
	v_mov_b32_e32 v129, v207
	v_mov_b32_e32 v130, v208
	v_mov_b32_e32 v131, v209
	v_add_u32_e32 v251, 0x48000, v250
	global_load_dwordx4 v[206:209], v251, s[44:45]
	v_lshlrev_b32_e32 v132, 16, v128
	v_and_b32_e32 v133, 0xffff0000, v128
	v_lshlrev_b32_e32 v134, 16, v129
	v_and_b32_e32 v135, 0xffff0000, v129
	v_lshlrev_b32_e32 v128, 16, v130
	v_and_b32_e32 v129, 0xffff0000, v130
	v_lshlrev_b32_e32 v130, 16, v131
	v_and_b32_e32 v131, 0xffff0000, v131
.LBB0_497:
	v_pk_add_f32 v[126:127], v[126:127], v[70:71]
	v_pk_add_f32 v[124:125], v[124:125], v[68:69]
	v_pk_add_f32 v[122:123], v[122:123], v[66:67]
	v_pk_add_f32 v[120:121], v[120:121], v[64:65]
	v_pk_add_f32 v[134:135], v[126:127], v[134:135]
	v_pk_add_f32 v[132:133], v[124:125], v[132:133]
	v_pk_add_f32 v[130:131], v[122:123], v[130:131]
	v_pk_add_f32 v[142:143], v[120:121], v[128:129]
	v_cvt_pk_bf16_f32 v120, v132, v133
	v_cvt_pk_bf16_f32 v121, v134, v135
	v_cvt_pk_bf16_f32 v122, v142, v143
	v_cvt_pk_bf16_f32 v123, v130, v131
	s_and_b64 vcc, exec, s[6:7]
	global_store_dwordx4 v[146:147], v[120:123], off
	s_cbranch_vccnz .LBB0_504
	s_nop 0
	v_lshlrev_b64 v[120:121], 12, v[152:153]
	v_lshl_add_u64 v[120:121], s[28:29], 0, v[120:121]
	v_cmp_gt_i32_e32 vcc, s70, v136
	s_nop 1
	v_cndmask_b32_e32 v121, v121, v139, vcc
	v_cndmask_b32_e32 v120, v120, v138, vcc
	v_lshl_add_u64 v[124:125], v[144:145], 2, v[120:121]
	global_load_dwordx4 v[120:123], v[124:125], off offset:16
	s_nop 0
	global_load_dwordx4 v[124:127], v[124:125], off
	s_waitcnt vmcnt(0)
	v_lshl_add_u64 v[128:129], v[144:145], 1, v[140:141]
	s_cbranch_execnz .LBB0_500
.LBB0_499:
	s_waitcnt vmcnt(9) lgkmcnt(0)
	v_mov_b32_e32 v120, v210
	v_mov_b32_e32 v121, v211
	v_mov_b32_e32 v122, v212
	v_mov_b32_e32 v123, v213
	v_add_u32_e32 v251, 0x48100, v250
	global_load_dwordx4 v[210:213], v251, s[44:45]
	v_lshlrev_b32_e32 v124, 16, v120
	v_and_b32_e32 v125, 0xffff0000, v120
	v_lshlrev_b32_e32 v126, 16, v121
	v_and_b32_e32 v127, 0xffff0000, v121
	v_lshlrev_b32_e32 v120, 16, v122
	v_and_b32_e32 v121, 0xffff0000, v122
	v_lshlrev_b32_e32 v122, 16, v123
	v_and_b32_e32 v123, 0xffff0000, v123
.LBB0_500:
	v_pk_add_f32 v[118:119], v[118:119], v[62:63]
	v_pk_add_f32 v[116:117], v[116:117], v[60:61]
	v_pk_add_f32 v[118:119], v[118:119], v[126:127]
	v_pk_add_f32 v[116:117], v[116:117], v[124:125]
	v_pk_add_f32 v[112:113], v[112:113], v[56:57]
	v_mul_f32_e32 v133, v133, v133
	v_pk_add_f32 v[120:121], v[112:113], v[120:121]
	v_mul_f32_e32 v112, v117, v117
	v_mul_f32_e32 v113, v119, v119
	v_fmac_f32_e32 v133, v132, v132
	v_mul_f32_e32 v132, v135, v135
	v_fmac_f32_e32 v112, v116, v116
	v_fmac_f32_e32 v113, v118, v118
	v_fmac_f32_e32 v132, v134, v134
	v_pk_add_f32 v[114:115], v[114:115], v[58:59]
	v_add_f32_e32 v112, v112, v113
	v_mul_f32_e32 v113, v121, v121
	v_add_f32_e32 v132, v133, v132
	v_mul_f32_e32 v133, v143, v143
	v_pk_add_f32 v[122:123], v[114:115], v[122:123]
	v_fmac_f32_e32 v113, v120, v120
	v_fmac_f32_e32 v133, v142, v142
	v_mul_f32_e32 v131, v131, v131
	v_add_f32_e32 v112, v113, v112
	v_mul_f32_e32 v113, v123, v123
	v_add_f32_e32 v132, v133, v132
	v_fmac_f32_e32 v131, v130, v130
	v_fmac_f32_e32 v113, v122, v122
	v_add_f32_e32 v130, v131, v132
	v_add_f32_e32 v112, v113, v112
	v_add_f32_e32 v112, v130, v112
	ds_bpermute_b32 v113, v149, v112
	v_cvt_pk_bf16_f32 v114, v116, v117
	v_cvt_pk_bf16_f32 v115, v118, v119
	v_cvt_pk_bf16_f32 v116, v120, v121
	v_cvt_pk_bf16_f32 v117, v122, v123
	s_waitcnt lgkmcnt(0)
	v_add_f32_e32 v112, v112, v113
	ds_bpermute_b32 v113, v150, v112
	global_store_dwordx4 v[128:129], v[114:117], off
	s_and_saveexec_b64 s[8:9], s[10:11]
	s_cbranch_execz .LBB0_502
	v_lshlrev_b64 v[114:115], 6, v[136:137]
	v_lshl_add_u64 v[114:115], s[40:41], 0, v[114:115]
	v_lshl_add_u64 v[114:115], s[52:53], 2, v[114:115]
	s_lshl_b32 s0, s68, 2
	v_lshl_add_u64 v[114:115], v[114:115], 0, s[0:1]
	s_waitcnt lgkmcnt(0)
	v_add_f32_e32 v112, v112, v113
	global_store_dword v[114:115], v112, off
.LBB0_502:
	s_or_b64 exec, exec, s[8:9]
	v_or_b32_e32 v120, 32, v172
	v_ashrrev_i32_e32 v121, 31, v120
	s_waitcnt lgkmcnt(0)
	v_lshlrev_b64 v[112:113], 12, v[120:121]
	s_and_b64 vcc, exec, s[6:7]
	v_lshl_add_u64 v[122:123], s[48:49], 0, v[112:113]
	v_cmp_gt_i32_e64 s[8:9], s70, v120
	v_subrev_u32_e32 v152, s70, v120
	s_cbranch_vccnz .LBB0_505
	v_lshlrev_b64 v[112:113], 12, v[152:153]
	v_lshl_add_u64 v[112:113], s[28:29], 0, v[112:113]
	v_cndmask_b32_e64 v113, v113, v123, s[8:9]
	v_cndmask_b32_e64 v112, v112, v122, s[8:9]
	v_lshl_add_u64 v[116:117], v[170:171], 2, v[112:113]
	global_load_dwordx4 v[112:115], v[116:117], off offset:16
	s_nop 0
	global_load_dwordx4 v[116:119], v[116:117], off
	s_waitcnt vmcnt(0)
	s_mov_b64 s[8:9], 0
	s_branch .LBB0_506

.LBB0_506:
	v_lshlrev_b64 v[124:125], 11, v[120:121]
	v_lshl_add_u64 v[124:125], s[44:45], 0, v[124:125]
	s_andn2_b64 vcc, exec, s[8:9]
	v_lshl_add_u64 v[128:129], v[170:171], 1, v[124:125]
	s_cbranch_vccnz .LBB0_508
	s_waitcnt vmcnt(11) lgkmcnt(0)
	v_mov_b32_e32 v112, v214
	v_mov_b32_e32 v113, v215
	v_mov_b32_e32 v114, v216
	v_mov_b32_e32 v115, v217
	v_add_u32_e32 v251, 0x50000, v250
	global_load_dwordx4 v[214:217], v251, s[44:45]
	v_lshlrev_b32_e32 v116, 16, v112
	v_and_b32_e32 v117, 0xffff0000, v112
	v_lshlrev_b32_e32 v118, 16, v113
	v_and_b32_e32 v119, 0xffff0000, v113
	v_lshlrev_b32_e32 v112, 16, v114
	v_and_b32_e32 v113, 0xffff0000, v114
	v_lshlrev_b32_e32 v114, 16, v115
	v_and_b32_e32 v115, 0xffff0000, v115
.LBB0_508:
	v_pk_add_f32 v[110:111], v[110:111], v[70:71]
	v_pk_add_f32 v[108:109], v[108:109], v[68:69]
	v_pk_add_f32 v[106:107], v[106:107], v[66:67]
	v_pk_add_f32 v[104:105], v[104:105], v[64:65]
	v_pk_add_f32 v[118:119], v[110:111], v[118:119]
	v_pk_add_f32 v[116:117], v[108:109], v[116:117]
	v_pk_add_f32 v[114:115], v[106:107], v[114:115]
	v_pk_add_f32 v[126:127], v[104:105], v[112:113]
	v_cvt_pk_bf16_f32 v104, v116, v117
	v_cvt_pk_bf16_f32 v105, v118, v119
	v_cvt_pk_bf16_f32 v106, v126, v127
	v_cvt_pk_bf16_f32 v107, v114, v115
	s_and_b64 vcc, exec, s[6:7]
	global_store_dwordx4 v[128:129], v[104:107], off
	s_cbranch_vccnz .LBB0_515
	s_nop 0
	v_lshlrev_b64 v[104:105], 12, v[152:153]
	v_lshl_add_u64 v[104:105], s[28:29], 0, v[104:105]
	v_cmp_gt_i32_e32 vcc, s70, v120
	s_nop 1
	v_cndmask_b32_e32 v105, v105, v123, vcc
	v_cndmask_b32_e32 v104, v104, v122, vcc
	v_lshl_add_u64 v[108:109], v[144:145], 2, v[104:105]
	global_load_dwordx4 v[104:107], v[108:109], off offset:16
	s_nop 0
	global_load_dwordx4 v[108:111], v[108:109], off
	s_waitcnt vmcnt(0)
	v_lshl_add_u64 v[112:113], v[144:145], 1, v[124:125]
	s_cbranch_execnz .LBB0_511
.LBB0_510:
	s_waitcnt vmcnt(12) lgkmcnt(0)
	v_mov_b32_e32 v104, v218
	v_mov_b32_e32 v105, v219
	v_mov_b32_e32 v106, v220
	v_mov_b32_e32 v107, v221
	v_add_u32_e32 v251, 0x50100, v250
	global_load_dwordx4 v[218:221], v251, s[44:45]
	v_lshlrev_b32_e32 v108, 16, v104
	v_and_b32_e32 v109, 0xffff0000, v104
	v_lshlrev_b32_e32 v110, 16, v105
	v_and_b32_e32 v111, 0xffff0000, v105
	v_lshlrev_b32_e32 v104, 16, v106
	v_and_b32_e32 v105, 0xffff0000, v106
	v_lshlrev_b32_e32 v106, 16, v107
	v_and_b32_e32 v107, 0xffff0000, v107
.LBB0_511:
	v_pk_add_f32 v[102:103], v[102:103], v[62:63]
	v_pk_add_f32 v[100:101], v[100:101], v[60:61]
	v_pk_add_f32 v[102:103], v[102:103], v[110:111]
	v_pk_add_f32 v[100:101], v[100:101], v[108:109]
	v_pk_add_f32 v[96:97], v[96:97], v[56:57]
	v_mul_f32_e32 v117, v117, v117
	v_pk_add_f32 v[104:105], v[96:97], v[104:105]
	v_mul_f32_e32 v96, v101, v101
	v_mul_f32_e32 v97, v103, v103
	v_fmac_f32_e32 v117, v116, v116
	v_mul_f32_e32 v116, v119, v119
	v_fmac_f32_e32 v96, v100, v100
	v_fmac_f32_e32 v97, v102, v102
	v_fmac_f32_e32 v116, v118, v118
	v_pk_add_f32 v[98:99], v[98:99], v[58:59]
	v_add_f32_e32 v96, v96, v97
	v_mul_f32_e32 v97, v105, v105
	v_add_f32_e32 v116, v117, v116
	v_mul_f32_e32 v117, v127, v127
	v_pk_add_f32 v[106:107], v[98:99], v[106:107]
	v_fmac_f32_e32 v97, v104, v104
	v_fmac_f32_e32 v117, v126, v126
	v_mul_f32_e32 v115, v115, v115
	v_add_f32_e32 v96, v97, v96
	v_mul_f32_e32 v97, v107, v107
	v_add_f32_e32 v116, v117, v116
	v_fmac_f32_e32 v115, v114, v114
	v_fmac_f32_e32 v97, v106, v106
	v_add_f32_e32 v114, v115, v116
	v_add_f32_e32 v96, v97, v96
	v_add_f32_e32 v96, v114, v96
	ds_bpermute_b32 v97, v149, v96
	v_cvt_pk_bf16_f32 v98, v100, v101
	v_cvt_pk_bf16_f32 v99, v102, v103
	v_cvt_pk_bf16_f32 v100, v104, v105
	v_cvt_pk_bf16_f32 v101, v106, v107
	s_waitcnt lgkmcnt(0)
	v_add_f32_e32 v96, v96, v97
	ds_bpermute_b32 v97, v150, v96
	global_store_dwordx4 v[112:113], v[98:101], off
	s_and_saveexec_b64 s[8:9], s[10:11]
	s_cbranch_execz .LBB0_513
	v_lshlrev_b64 v[98:99], 6, v[120:121]
	v_lshl_add_u64 v[98:99], s[40:41], 0, v[98:99]
	v_lshl_add_u64 v[98:99], s[52:53], 2, v[98:99]
	s_lshl_b32 s0, s68, 2
	v_lshl_add_u64 v[98:99], v[98:99], 0, s[0:1]
	s_waitcnt lgkmcnt(0)
	v_add_f32_e32 v96, v96, v97
	global_store_dword v[98:99], v96, off
.LBB0_513:
	s_or_b64 exec, exec, s[8:9]
	v_or_b32_e32 v104, 48, v172
	v_ashrrev_i32_e32 v105, 31, v104
	s_waitcnt lgkmcnt(0)
	v_lshlrev_b64 v[96:97], 12, v[104:105]
	s_and_b64 vcc, exec, s[6:7]
	v_lshl_add_u64 v[106:107], s[48:49], 0, v[96:97]
	v_cmp_gt_i32_e64 s[8:9], s70, v104
	v_subrev_u32_e32 v152, s70, v104
	s_cbranch_vccnz .LBB0_516
	v_lshlrev_b64 v[96:97], 12, v[152:153]
	v_lshl_add_u64 v[96:97], s[28:29], 0, v[96:97]
	v_cndmask_b32_e64 v97, v97, v107, s[8:9]
	v_cndmask_b32_e64 v96, v96, v106, s[8:9]
	v_lshl_add_u64 v[100:101], v[170:171], 2, v[96:97]
	global_load_dwordx4 v[96:99], v[100:101], off offset:16
	s_nop 0
	global_load_dwordx4 v[100:103], v[100:101], off
	s_waitcnt vmcnt(0)
	s_mov_b64 s[8:9], 0
	s_branch .LBB0_517

.LBB0_517:
	v_lshlrev_b64 v[108:109], 11, v[104:105]
	v_lshl_add_u64 v[108:109], s[44:45], 0, v[108:109]
	s_andn2_b64 vcc, exec, s[8:9]
	v_lshl_add_u64 v[112:113], v[170:171], 1, v[108:109]
	s_cbranch_vccnz .LBB0_519
	s_waitcnt vmcnt(14) lgkmcnt(0)
	v_mov_b32_e32 v96, v222
	v_mov_b32_e32 v97, v223
	v_mov_b32_e32 v98, v224
	v_mov_b32_e32 v99, v225
	v_add_u32_e32 v251, 0x58000, v250
	global_load_dwordx4 v[222:225], v251, s[44:45]
	v_lshlrev_b32_e32 v100, 16, v96
	v_and_b32_e32 v101, 0xffff0000, v96
	v_lshlrev_b32_e32 v102, 16, v97
	v_and_b32_e32 v103, 0xffff0000, v97
	v_lshlrev_b32_e32 v96, 16, v98
	v_and_b32_e32 v97, 0xffff0000, v98
	v_lshlrev_b32_e32 v98, 16, v99
	v_and_b32_e32 v99, 0xffff0000, v99
.LBB0_519:
	v_pk_add_f32 v[94:95], v[94:95], v[70:71]
	v_pk_add_f32 v[92:93], v[92:93], v[68:69]
	v_pk_add_f32 v[90:91], v[90:91], v[66:67]
	v_pk_add_f32 v[88:89], v[88:89], v[64:65]
	v_pk_add_f32 v[102:103], v[94:95], v[102:103]
	v_pk_add_f32 v[100:101], v[92:93], v[100:101]
	v_pk_add_f32 v[98:99], v[90:91], v[98:99]
	v_pk_add_f32 v[110:111], v[88:89], v[96:97]
	v_cvt_pk_bf16_f32 v88, v100, v101
	v_cvt_pk_bf16_f32 v89, v102, v103
	v_cvt_pk_bf16_f32 v90, v110, v111
	v_cvt_pk_bf16_f32 v91, v98, v99
	s_and_b64 vcc, exec, s[6:7]
	global_store_dwordx4 v[112:113], v[88:91], off
	s_cbranch_vccnz .LBB0_526
	s_nop 0
	v_lshlrev_b64 v[88:89], 12, v[152:153]
	v_lshl_add_u64 v[88:89], s[28:29], 0, v[88:89]
	v_cmp_gt_i32_e32 vcc, s70, v104
	s_nop 1
	v_cndmask_b32_e32 v89, v89, v107, vcc
	v_cndmask_b32_e32 v88, v88, v106, vcc
	v_lshl_add_u64 v[92:93], v[144:145], 2, v[88:89]
	global_load_dwordx4 v[88:91], v[92:93], off offset:16
	s_nop 0
	global_load_dwordx4 v[92:95], v[92:93], off
	s_waitcnt vmcnt(0)
	v_lshl_add_u64 v[96:97], v[144:145], 1, v[108:109]
	s_cbranch_execnz .LBB0_522
.LBB0_521:
	s_waitcnt vmcnt(15) lgkmcnt(0)
	v_mov_b32_e32 v88, v238
	v_mov_b32_e32 v89, v239
	v_mov_b32_e32 v90, v240
	v_mov_b32_e32 v91, v241
	v_add_u32_e32 v251, 0x58100, v250
	global_load_dwordx4 v[238:241], v251, s[44:45]
	v_lshlrev_b32_e32 v92, 16, v88
	v_and_b32_e32 v93, 0xffff0000, v88
	v_lshlrev_b32_e32 v94, 16, v89
	v_and_b32_e32 v95, 0xffff0000, v89
	v_lshlrev_b32_e32 v88, 16, v90
	v_and_b32_e32 v89, 0xffff0000, v90
	v_lshlrev_b32_e32 v90, 16, v91
	v_and_b32_e32 v91, 0xffff0000, v91
.LBB0_522:
	v_pk_add_f32 v[86:87], v[86:87], v[62:63]
	v_pk_add_f32 v[84:85], v[84:85], v[60:61]
	v_pk_add_f32 v[86:87], v[86:87], v[94:95]
	v_pk_add_f32 v[84:85], v[84:85], v[92:93]
	v_pk_add_f32 v[80:81], v[80:81], v[56:57]
	v_mul_f32_e32 v101, v101, v101
	v_pk_add_f32 v[88:89], v[80:81], v[88:89]
	v_mul_f32_e32 v80, v85, v85
	v_mul_f32_e32 v81, v87, v87
	v_fmac_f32_e32 v101, v100, v100
	v_mul_f32_e32 v100, v103, v103
	v_fmac_f32_e32 v80, v84, v84
	v_fmac_f32_e32 v81, v86, v86
	v_fmac_f32_e32 v100, v102, v102
	v_pk_add_f32 v[82:83], v[82:83], v[58:59]
	v_add_f32_e32 v80, v80, v81
	v_mul_f32_e32 v81, v89, v89
	v_add_f32_e32 v100, v101, v100
	v_mul_f32_e32 v101, v111, v111
	v_pk_add_f32 v[90:91], v[82:83], v[90:91]
	v_fmac_f32_e32 v81, v88, v88
	v_fmac_f32_e32 v101, v110, v110
	v_mul_f32_e32 v99, v99, v99
	v_add_f32_e32 v80, v81, v80
	v_mul_f32_e32 v81, v91, v91
	v_add_f32_e32 v100, v101, v100
	v_fmac_f32_e32 v99, v98, v98
	v_fmac_f32_e32 v81, v90, v90
	v_add_f32_e32 v98, v99, v100
	v_add_f32_e32 v80, v81, v80
	v_add_f32_e32 v80, v98, v80
	ds_bpermute_b32 v81, v149, v80
	v_cvt_pk_bf16_f32 v82, v84, v85
	v_cvt_pk_bf16_f32 v83, v86, v87
	v_cvt_pk_bf16_f32 v84, v88, v89
	v_cvt_pk_bf16_f32 v85, v90, v91
	s_waitcnt lgkmcnt(0)
	v_add_f32_e32 v80, v80, v81
	ds_bpermute_b32 v81, v150, v80
	global_store_dwordx4 v[96:97], v[82:85], off
	s_and_saveexec_b64 s[8:9], s[10:11]
	s_cbranch_execz .LBB0_524
	v_lshlrev_b64 v[82:83], 6, v[104:105]
	v_lshl_add_u64 v[82:83], s[40:41], 0, v[82:83]
	v_lshl_add_u64 v[82:83], s[52:53], 2, v[82:83]
	s_lshl_b32 s0, s68, 2
	v_lshl_add_u64 v[82:83], v[82:83], 0, s[0:1]
	s_waitcnt lgkmcnt(0)
	v_add_f32_e32 v80, v80, v81
	global_store_dword v[82:83], v80, off
.LBB0_524:
	s_or_b64 exec, exec, s[8:9]
	v_add_u32_e32 v88, 0x80, v172
	v_ashrrev_i32_e32 v89, 31, v88
	s_waitcnt lgkmcnt(0)
	v_lshlrev_b64 v[80:81], 12, v[88:89]
	s_and_b64 vcc, exec, s[6:7]
	v_lshl_add_u64 v[90:91], s[48:49], 0, v[80:81]
	v_cmp_gt_i32_e64 s[8:9], s70, v88
	v_subrev_u32_e32 v152, s70, v88
	s_cbranch_vccnz .LBB0_527
	v_lshlrev_b64 v[80:81], 12, v[152:153]
	v_lshl_add_u64 v[80:81], s[28:29], 0, v[80:81]
	v_cndmask_b32_e64 v81, v81, v91, s[8:9]
	v_cndmask_b32_e64 v80, v80, v90, s[8:9]
	v_lshl_add_u64 v[84:85], v[170:171], 2, v[80:81]
	global_load_dwordx4 v[80:83], v[84:85], off offset:16
	s_nop 0
	global_load_dwordx4 v[84:87], v[84:85], off
	s_waitcnt vmcnt(0)
	s_mov_b64 s[8:9], 0
	s_branch .LBB0_528

.LBB0_528:
	v_lshlrev_b64 v[92:93], 11, v[88:89]
	v_lshl_add_u64 v[92:93], s[44:45], 0, v[92:93]
	s_andn2_b64 vcc, exec, s[8:9]
	v_lshl_add_u64 v[96:97], v[170:171], 1, v[92:93]
	s_cbranch_vccnz .LBB0_530
	s_waitcnt vmcnt(17) lgkmcnt(0)
	v_mov_b32_e32 v80, v198
	v_mov_b32_e32 v81, v199
	v_mov_b32_e32 v82, v200
	v_mov_b32_e32 v83, v201
	v_lshlrev_b32_e32 v84, 16, v80
	v_and_b32_e32 v85, 0xffff0000, v80
	v_lshlrev_b32_e32 v86, 16, v81
	v_and_b32_e32 v87, 0xffff0000, v81
	v_lshlrev_b32_e32 v80, 16, v82
	v_and_b32_e32 v81, 0xffff0000, v82
	v_lshlrev_b32_e32 v82, 16, v83
	v_and_b32_e32 v83, 0xffff0000, v83
.LBB0_530:
	v_pk_add_f32 v[78:79], v[78:79], v[70:71]
	v_pk_add_f32 v[76:77], v[76:77], v[68:69]
	v_pk_add_f32 v[74:75], v[74:75], v[66:67]
	v_pk_add_f32 v[72:73], v[72:73], v[64:65]
	v_pk_add_f32 v[86:87], v[78:79], v[86:87]
	v_pk_add_f32 v[84:85], v[76:77], v[84:85]
	v_pk_add_f32 v[82:83], v[74:75], v[82:83]
	v_pk_add_f32 v[94:95], v[72:73], v[80:81]
	v_cvt_pk_bf16_f32 v72, v84, v85
	v_cvt_pk_bf16_f32 v73, v86, v87
	v_cvt_pk_bf16_f32 v74, v94, v95
	v_cvt_pk_bf16_f32 v75, v82, v83
	s_and_b64 vcc, exec, s[6:7]
	global_store_dwordx4 v[96:97], v[72:75], off
	s_cbranch_vccnz .LBB0_537
	s_nop 0
	v_lshlrev_b64 v[72:73], 12, v[152:153]
	v_lshl_add_u64 v[72:73], s[28:29], 0, v[72:73]
	v_cmp_gt_i32_e32 vcc, s70, v88
	s_nop 1
	v_cndmask_b32_e32 v73, v73, v91, vcc
	v_cndmask_b32_e32 v72, v72, v90, vcc
	v_lshl_add_u64 v[76:77], v[144:145], 2, v[72:73]
	global_load_dwordx4 v[72:75], v[76:77], off offset:16
	s_nop 0
	global_load_dwordx4 v[76:79], v[76:77], off
	s_waitcnt vmcnt(0)
	v_lshl_add_u64 v[80:81], v[144:145], 1, v[92:93]
	s_cbranch_execnz .LBB0_533
.LBB0_532:
	s_waitcnt vmcnt(16) lgkmcnt(0)
	v_mov_b32_e32 v72, v202
	v_mov_b32_e32 v73, v203
	v_mov_b32_e32 v74, v204
	v_mov_b32_e32 v75, v205
	v_lshlrev_b32_e32 v76, 16, v72
	v_and_b32_e32 v77, 0xffff0000, v72
	v_lshlrev_b32_e32 v78, 16, v73
	v_and_b32_e32 v79, 0xffff0000, v73
	v_lshlrev_b32_e32 v72, 16, v74
	v_and_b32_e32 v73, 0xffff0000, v74
	v_lshlrev_b32_e32 v74, 16, v75
	v_and_b32_e32 v75, 0xffff0000, v75
.LBB0_533:
	v_pk_add_f32 v[54:55], v[54:55], v[62:63]
	v_pk_add_f32 v[52:53], v[52:53], v[60:61]
	v_pk_add_f32 v[54:55], v[54:55], v[78:79]
	v_pk_add_f32 v[52:53], v[52:53], v[76:77]
	v_pk_add_f32 v[48:49], v[48:49], v[56:57]
	v_mul_f32_e32 v85, v85, v85
	v_pk_add_f32 v[72:73], v[48:49], v[72:73]
	v_mul_f32_e32 v48, v53, v53
	v_mul_f32_e32 v49, v55, v55
	v_fmac_f32_e32 v85, v84, v84
	v_mul_f32_e32 v84, v87, v87
	v_fmac_f32_e32 v48, v52, v52
	v_fmac_f32_e32 v49, v54, v54
	v_fmac_f32_e32 v84, v86, v86
	v_pk_add_f32 v[50:51], v[50:51], v[58:59]
	v_add_f32_e32 v48, v48, v49
	v_mul_f32_e32 v49, v73, v73
	v_add_f32_e32 v84, v85, v84
	v_mul_f32_e32 v85, v95, v95
	v_pk_add_f32 v[74:75], v[50:51], v[74:75]
	v_fmac_f32_e32 v49, v72, v72
	v_fmac_f32_e32 v85, v94, v94
	v_mul_f32_e32 v83, v83, v83
	v_add_f32_e32 v48, v49, v48
	v_mul_f32_e32 v49, v75, v75
	v_add_f32_e32 v84, v85, v84
	v_fmac_f32_e32 v83, v82, v82
	v_fmac_f32_e32 v49, v74, v74
	v_add_f32_e32 v82, v83, v84
	v_add_f32_e32 v48, v49, v48
	v_add_f32_e32 v48, v82, v48
	ds_bpermute_b32 v49, v149, v48
	v_cvt_pk_bf16_f32 v50, v52, v53
	v_cvt_pk_bf16_f32 v51, v54, v55
	v_cvt_pk_bf16_f32 v52, v72, v73
	v_cvt_pk_bf16_f32 v53, v74, v75
	s_waitcnt lgkmcnt(0)
	v_add_f32_e32 v48, v48, v49
	ds_bpermute_b32 v49, v150, v48
	global_store_dwordx4 v[80:81], v[50:53], off
	s_and_saveexec_b64 s[8:9], s[10:11]
	s_cbranch_execz .LBB0_535
	v_lshlrev_b64 v[50:51], 6, v[88:89]
	v_lshl_add_u64 v[50:51], s[40:41], 0, v[50:51]
	v_lshl_add_u64 v[50:51], s[52:53], 2, v[50:51]
	s_lshl_b32 s0, s68, 2
	v_lshl_add_u64 v[50:51], v[50:51], 0, s[0:1]
	s_waitcnt lgkmcnt(0)
	v_add_f32_e32 v48, v48, v49
	global_store_dword v[50:51], v48, off
.LBB0_535:
	s_or_b64 exec, exec, s[8:9]
	v_add_u32_e32 v72, 0x90, v172
	v_ashrrev_i32_e32 v73, 31, v72
	s_waitcnt lgkmcnt(0)
	v_lshlrev_b64 v[48:49], 12, v[72:73]
	s_and_b64 vcc, exec, s[6:7]
	v_lshl_add_u64 v[74:75], s[48:49], 0, v[48:49]
	v_cmp_gt_i32_e64 s[8:9], s70, v72
	v_subrev_u32_e32 v152, s70, v72
	s_cbranch_vccnz .LBB0_538
	v_lshlrev_b64 v[48:49], 12, v[152:153]
	v_lshl_add_u64 v[48:49], s[28:29], 0, v[48:49]
	v_cndmask_b32_e64 v49, v49, v75, s[8:9]
	v_cndmask_b32_e64 v48, v48, v74, s[8:9]
	v_lshl_add_u64 v[52:53], v[170:171], 2, v[48:49]
	global_load_dwordx4 v[48:51], v[52:53], off offset:16
	s_nop 0
	global_load_dwordx4 v[52:55], v[52:53], off
	s_waitcnt vmcnt(0)
	s_mov_b64 s[8:9], 0
	s_branch .LBB0_539

.LBB0_539:
	v_lshlrev_b64 v[76:77], 11, v[72:73]
	v_lshl_add_u64 v[76:77], s[44:45], 0, v[76:77]
	s_andn2_b64 vcc, exec, s[8:9]
	v_lshl_add_u64 v[80:81], v[170:171], 1, v[76:77]
	s_cbranch_vccnz .LBB0_541
	s_waitcnt vmcnt(15) lgkmcnt(0)
	v_mov_b32_e32 v48, v206
	v_mov_b32_e32 v49, v207
	v_mov_b32_e32 v50, v208
	v_mov_b32_e32 v51, v209
	v_lshlrev_b32_e32 v52, 16, v48
	v_and_b32_e32 v53, 0xffff0000, v48
	v_lshlrev_b32_e32 v54, 16, v49
	v_and_b32_e32 v55, 0xffff0000, v49
	v_lshlrev_b32_e32 v48, 16, v50
	v_and_b32_e32 v49, 0xffff0000, v50
	v_lshlrev_b32_e32 v50, 16, v51
	v_and_b32_e32 v51, 0xffff0000, v51
.LBB0_541:
	v_pk_add_f32 v[46:47], v[46:47], v[70:71]
	v_pk_add_f32 v[44:45], v[44:45], v[68:69]
	v_pk_add_f32 v[42:43], v[42:43], v[66:67]
	v_pk_add_f32 v[40:41], v[40:41], v[64:65]
	v_pk_add_f32 v[54:55], v[46:47], v[54:55]
	v_pk_add_f32 v[52:53], v[44:45], v[52:53]
	v_pk_add_f32 v[50:51], v[42:43], v[50:51]
	v_pk_add_f32 v[78:79], v[40:41], v[48:49]
	v_cvt_pk_bf16_f32 v40, v52, v53
	v_cvt_pk_bf16_f32 v41, v54, v55
	v_cvt_pk_bf16_f32 v42, v78, v79
	v_cvt_pk_bf16_f32 v43, v50, v51
	s_and_b64 vcc, exec, s[6:7]
	global_store_dwordx4 v[80:81], v[40:43], off
	s_cbranch_vccnz .LBB0_548
	s_nop 0
	v_lshlrev_b64 v[40:41], 12, v[152:153]
	v_lshl_add_u64 v[40:41], s[28:29], 0, v[40:41]
	v_cmp_gt_i32_e32 vcc, s70, v72
	s_nop 1
	v_cndmask_b32_e32 v41, v41, v75, vcc
	v_cndmask_b32_e32 v40, v40, v74, vcc
	v_lshl_add_u64 v[44:45], v[144:145], 2, v[40:41]
	global_load_dwordx4 v[40:43], v[44:45], off offset:16
	s_nop 0
	global_load_dwordx4 v[44:47], v[44:45], off
	s_waitcnt vmcnt(0)
	v_lshl_add_u64 v[48:49], v[144:145], 1, v[76:77]
	s_cbranch_execnz .LBB0_544
.LBB0_543:
	s_waitcnt vmcnt(14) lgkmcnt(0)
	v_mov_b32_e32 v40, v210
	v_mov_b32_e32 v41, v211
	v_mov_b32_e32 v42, v212
	v_mov_b32_e32 v43, v213
	v_lshlrev_b32_e32 v44, 16, v40
	v_and_b32_e32 v45, 0xffff0000, v40
	v_lshlrev_b32_e32 v46, 16, v41
	v_and_b32_e32 v47, 0xffff0000, v41
	v_lshlrev_b32_e32 v40, 16, v42
	v_and_b32_e32 v41, 0xffff0000, v42
	v_lshlrev_b32_e32 v42, 16, v43
	v_and_b32_e32 v43, 0xffff0000, v43
.LBB0_544:
	v_pk_add_f32 v[38:39], v[38:39], v[62:63]
	v_pk_add_f32 v[36:37], v[36:37], v[60:61]
	v_pk_add_f32 v[38:39], v[38:39], v[46:47]
	v_pk_add_f32 v[36:37], v[36:37], v[44:45]
	v_pk_add_f32 v[32:33], v[32:33], v[56:57]
	v_mul_f32_e32 v53, v53, v53
	v_pk_add_f32 v[40:41], v[32:33], v[40:41]
	v_mul_f32_e32 v32, v37, v37
	v_mul_f32_e32 v33, v39, v39
	v_fmac_f32_e32 v53, v52, v52
	v_mul_f32_e32 v52, v55, v55
	v_fmac_f32_e32 v32, v36, v36
	v_fmac_f32_e32 v33, v38, v38
	v_fmac_f32_e32 v52, v54, v54
	v_pk_add_f32 v[34:35], v[34:35], v[58:59]
	v_add_f32_e32 v32, v32, v33
	v_mul_f32_e32 v33, v41, v41
	v_add_f32_e32 v52, v53, v52
	v_mul_f32_e32 v53, v79, v79
	v_pk_add_f32 v[42:43], v[34:35], v[42:43]
	v_fmac_f32_e32 v33, v40, v40
	v_fmac_f32_e32 v53, v78, v78
	v_mul_f32_e32 v51, v51, v51
	v_add_f32_e32 v32, v33, v32
	v_mul_f32_e32 v33, v43, v43
	v_add_f32_e32 v52, v53, v52
	v_fmac_f32_e32 v51, v50, v50
	v_fmac_f32_e32 v33, v42, v42
	v_add_f32_e32 v50, v51, v52
	v_add_f32_e32 v32, v33, v32
	v_add_f32_e32 v32, v50, v32
	ds_bpermute_b32 v33, v149, v32
	v_cvt_pk_bf16_f32 v34, v36, v37
	v_cvt_pk_bf16_f32 v35, v38, v39
	v_cvt_pk_bf16_f32 v36, v40, v41
	v_cvt_pk_bf16_f32 v37, v42, v43
	s_waitcnt lgkmcnt(0)
	v_add_f32_e32 v32, v32, v33
	ds_bpermute_b32 v33, v150, v32
	global_store_dwordx4 v[48:49], v[34:37], off
	s_and_saveexec_b64 s[8:9], s[10:11]
	s_cbranch_execz .LBB0_546
	v_lshlrev_b64 v[34:35], 6, v[72:73]
	v_lshl_add_u64 v[34:35], s[40:41], 0, v[34:35]
	v_lshl_add_u64 v[34:35], s[52:53], 2, v[34:35]
	s_lshl_b32 s0, s68, 2
	v_lshl_add_u64 v[34:35], v[34:35], 0, s[0:1]
	s_waitcnt lgkmcnt(0)
	v_add_f32_e32 v32, v32, v33
	global_store_dword v[34:35], v32, off
.LBB0_546:
	s_or_b64 exec, exec, s[8:9]
	v_add_u32_e32 v40, 0xa0, v172
	v_ashrrev_i32_e32 v41, 31, v40
	s_waitcnt lgkmcnt(0)
	v_lshlrev_b64 v[32:33], 12, v[40:41]
	s_and_b64 vcc, exec, s[6:7]
	v_lshl_add_u64 v[42:43], s[48:49], 0, v[32:33]
	v_cmp_gt_i32_e64 s[8:9], s70, v40
	v_subrev_u32_e32 v152, s70, v40
	s_cbranch_vccnz .LBB0_549
	v_lshlrev_b64 v[32:33], 12, v[152:153]
	v_lshl_add_u64 v[32:33], s[28:29], 0, v[32:33]
	v_cndmask_b32_e64 v33, v33, v43, s[8:9]
	v_cndmask_b32_e64 v32, v32, v42, s[8:9]
	v_lshl_add_u64 v[36:37], v[170:171], 2, v[32:33]
	global_load_dwordx4 v[32:35], v[36:37], off offset:16
	s_nop 0
	global_load_dwordx4 v[36:39], v[36:37], off
	s_waitcnt vmcnt(0)
	s_mov_b64 s[8:9], 0
	s_branch .LBB0_550

.LBB0_550:
	v_lshlrev_b64 v[44:45], 11, v[40:41]
	v_lshl_add_u64 v[44:45], s[44:45], 0, v[44:45]
	s_andn2_b64 vcc, exec, s[8:9]
	v_lshl_add_u64 v[48:49], v[170:171], 1, v[44:45]
	s_cbranch_vccnz .LBB0_552
	s_waitcnt vmcnt(13) lgkmcnt(0)
	v_mov_b32_e32 v32, v214
	v_mov_b32_e32 v33, v215
	v_mov_b32_e32 v34, v216
	v_mov_b32_e32 v35, v217
	v_lshlrev_b32_e32 v36, 16, v32
	v_and_b32_e32 v37, 0xffff0000, v32
	v_lshlrev_b32_e32 v38, 16, v33
	v_and_b32_e32 v39, 0xffff0000, v33
	v_lshlrev_b32_e32 v32, 16, v34
	v_and_b32_e32 v33, 0xffff0000, v34
	v_lshlrev_b32_e32 v34, 16, v35
	v_and_b32_e32 v35, 0xffff0000, v35
.LBB0_552:
	v_pk_add_f32 v[30:31], v[30:31], v[70:71]
	v_pk_add_f32 v[28:29], v[28:29], v[68:69]
	v_pk_add_f32 v[26:27], v[26:27], v[66:67]
	v_pk_add_f32 v[24:25], v[24:25], v[64:65]
	v_pk_add_f32 v[38:39], v[30:31], v[38:39]
	v_pk_add_f32 v[36:37], v[28:29], v[36:37]
	v_pk_add_f32 v[34:35], v[26:27], v[34:35]
	v_pk_add_f32 v[46:47], v[24:25], v[32:33]
	v_cvt_pk_bf16_f32 v24, v36, v37
	v_cvt_pk_bf16_f32 v25, v38, v39
	v_cvt_pk_bf16_f32 v26, v46, v47
	v_cvt_pk_bf16_f32 v27, v34, v35
	s_and_b64 vcc, exec, s[6:7]
	global_store_dwordx4 v[48:49], v[24:27], off
	s_cbranch_vccnz .LBB0_559
	s_nop 0
	v_lshlrev_b64 v[24:25], 12, v[152:153]
	v_lshl_add_u64 v[24:25], s[28:29], 0, v[24:25]
	v_cmp_gt_i32_e32 vcc, s70, v40
	s_nop 1
	v_cndmask_b32_e32 v25, v25, v43, vcc
	v_cndmask_b32_e32 v24, v24, v42, vcc
	v_lshl_add_u64 v[28:29], v[144:145], 2, v[24:25]
	global_load_dwordx4 v[24:27], v[28:29], off offset:16
	s_nop 0
	global_load_dwordx4 v[28:31], v[28:29], off
	s_waitcnt vmcnt(0)
	v_lshl_add_u64 v[32:33], v[144:145], 1, v[44:45]
	s_cbranch_execnz .LBB0_555
.LBB0_554:
	s_waitcnt vmcnt(12) lgkmcnt(0)
	v_mov_b32_e32 v24, v218
	v_mov_b32_e32 v25, v219
	v_mov_b32_e32 v26, v220
	v_mov_b32_e32 v27, v221
	v_lshlrev_b32_e32 v28, 16, v24
	v_and_b32_e32 v29, 0xffff0000, v24
	v_lshlrev_b32_e32 v30, 16, v25
	v_and_b32_e32 v31, 0xffff0000, v25
	v_lshlrev_b32_e32 v24, 16, v26
	v_and_b32_e32 v25, 0xffff0000, v26
	v_lshlrev_b32_e32 v26, 16, v27
	v_and_b32_e32 v27, 0xffff0000, v27
.LBB0_555:
	v_pk_add_f32 v[22:23], v[22:23], v[62:63]
	v_pk_add_f32 v[20:21], v[20:21], v[60:61]
	v_pk_add_f32 v[22:23], v[22:23], v[30:31]
	v_pk_add_f32 v[20:21], v[20:21], v[28:29]
	v_pk_add_f32 v[16:17], v[16:17], v[56:57]
	v_mul_f32_e32 v37, v37, v37
	v_pk_add_f32 v[24:25], v[16:17], v[24:25]
	v_mul_f32_e32 v16, v21, v21
	v_mul_f32_e32 v17, v23, v23
	v_fmac_f32_e32 v37, v36, v36
	v_mul_f32_e32 v36, v39, v39
	v_fmac_f32_e32 v16, v20, v20
	v_fmac_f32_e32 v17, v22, v22
	v_fmac_f32_e32 v36, v38, v38
	v_pk_add_f32 v[18:19], v[18:19], v[58:59]
	v_add_f32_e32 v16, v16, v17
	v_mul_f32_e32 v17, v25, v25
	v_add_f32_e32 v36, v37, v36
	v_mul_f32_e32 v37, v47, v47
	v_pk_add_f32 v[26:27], v[18:19], v[26:27]
	v_fmac_f32_e32 v17, v24, v24
	v_fmac_f32_e32 v37, v46, v46
	v_mul_f32_e32 v35, v35, v35
	v_add_f32_e32 v16, v17, v16
	v_mul_f32_e32 v17, v27, v27
	v_add_f32_e32 v36, v37, v36
	v_fmac_f32_e32 v35, v34, v34
	v_fmac_f32_e32 v17, v26, v26
	v_add_f32_e32 v34, v35, v36
	v_add_f32_e32 v16, v17, v16
	v_add_f32_e32 v16, v34, v16
	ds_bpermute_b32 v17, v149, v16
	v_cvt_pk_bf16_f32 v18, v20, v21
	v_cvt_pk_bf16_f32 v19, v22, v23
	v_cvt_pk_bf16_f32 v20, v24, v25
	v_cvt_pk_bf16_f32 v21, v26, v27
	s_waitcnt lgkmcnt(0)
	v_add_f32_e32 v16, v16, v17
	ds_bpermute_b32 v17, v150, v16
	global_store_dwordx4 v[32:33], v[18:21], off
	s_and_saveexec_b64 s[8:9], s[10:11]
	s_cbranch_execz .LBB0_557
	v_lshlrev_b64 v[18:19], 6, v[40:41]
	v_lshl_add_u64 v[18:19], s[40:41], 0, v[18:19]
	v_lshl_add_u64 v[18:19], s[52:53], 2, v[18:19]
	s_lshl_b32 s0, s68, 2
	v_lshl_add_u64 v[18:19], v[18:19], 0, s[0:1]
	s_waitcnt lgkmcnt(0)
	v_add_f32_e32 v16, v16, v17
	global_store_dword v[18:19], v16, off
.LBB0_557:
	s_or_b64 exec, exec, s[8:9]
	v_add_u32_e32 v24, 0xb0, v172
	v_ashrrev_i32_e32 v25, 31, v24
	s_waitcnt lgkmcnt(0)
	v_lshlrev_b64 v[16:17], 12, v[24:25]
	s_and_b64 vcc, exec, s[6:7]
	v_lshl_add_u64 v[26:27], s[48:49], 0, v[16:17]
	v_cmp_gt_i32_e64 s[8:9], s70, v24
	v_subrev_u32_e32 v152, s70, v24
	s_cbranch_vccnz .LBB0_560
	v_lshlrev_b64 v[16:17], 12, v[152:153]
	v_lshl_add_u64 v[16:17], s[28:29], 0, v[16:17]
	v_cndmask_b32_e64 v17, v17, v27, s[8:9]
	v_cndmask_b32_e64 v16, v16, v26, s[8:9]
	v_lshl_add_u64 v[20:21], v[170:171], 2, v[16:17]
	global_load_dwordx4 v[16:19], v[20:21], off offset:16
	s_nop 0
	global_load_dwordx4 v[20:23], v[20:21], off
	s_waitcnt vmcnt(0)
	s_mov_b64 s[8:9], 0
	s_branch .LBB0_561

.LBB0_561:
	v_lshlrev_b64 v[28:29], 11, v[24:25]
	v_lshl_add_u64 v[28:29], s[44:45], 0, v[28:29]
	s_andn2_b64 vcc, exec, s[8:9]
	v_lshl_add_u64 v[32:33], v[170:171], 1, v[28:29]
	s_cbranch_vccnz .LBB0_563
	s_waitcnt vmcnt(11) lgkmcnt(0)
	v_mov_b32_e32 v16, v222
	v_mov_b32_e32 v17, v223
	v_mov_b32_e32 v18, v224
	v_mov_b32_e32 v19, v225
	v_lshlrev_b32_e32 v20, 16, v16
	v_and_b32_e32 v21, 0xffff0000, v16
	v_lshlrev_b32_e32 v22, 16, v17
	v_and_b32_e32 v23, 0xffff0000, v17
	v_lshlrev_b32_e32 v16, 16, v18
	v_and_b32_e32 v17, 0xffff0000, v18
	v_lshlrev_b32_e32 v18, 16, v19
	v_and_b32_e32 v19, 0xffff0000, v19
.LBB0_563:
	v_pk_add_f32 v[14:15], v[14:15], v[70:71]
	v_pk_add_f32 v[12:13], v[12:13], v[68:69]
	v_pk_add_f32 v[10:11], v[10:11], v[66:67]
	v_pk_add_f32 v[8:9], v[8:9], v[64:65]
	v_pk_add_f32 v[22:23], v[14:15], v[22:23]
	v_pk_add_f32 v[20:21], v[12:13], v[20:21]
	v_pk_add_f32 v[18:19], v[10:11], v[18:19]
	v_pk_add_f32 v[30:31], v[8:9], v[16:17]
	v_cvt_pk_bf16_f32 v8, v20, v21
	v_cvt_pk_bf16_f32 v9, v22, v23
	v_cvt_pk_bf16_f32 v10, v30, v31
	v_cvt_pk_bf16_f32 v11, v18, v19
	s_and_b64 vcc, exec, s[6:7]
	global_store_dwordx4 v[32:33], v[8:11], off
	s_cbranch_vccnz .LBB0_571
	s_nop 0
	v_lshlrev_b64 v[8:9], 12, v[152:153]
	v_lshl_add_u64 v[8:9], s[28:29], 0, v[8:9]
	v_cmp_gt_i32_e32 vcc, s70, v24
	s_nop 1
	v_cndmask_b32_e32 v9, v9, v27, vcc
	v_cndmask_b32_e32 v8, v8, v26, vcc
	v_lshl_add_u64 v[12:13], v[144:145], 2, v[8:9]
	global_load_dwordx4 v[8:11], v[12:13], off offset:16
	s_nop 0
	global_load_dwordx4 v[12:15], v[12:13], off
	s_waitcnt vmcnt(0)
	v_lshl_add_u64 v[16:17], v[144:145], 1, v[28:29]
	s_cbranch_execnz .LBB0_566
.LBB0_565:
	s_waitcnt vmcnt(10) lgkmcnt(0)
	v_mov_b32_e32 v8, v238
	v_mov_b32_e32 v9, v239
	v_mov_b32_e32 v10, v240
	v_mov_b32_e32 v11, v241
	v_lshlrev_b32_e32 v12, 16, v8
	v_and_b32_e32 v13, 0xffff0000, v8
	v_lshlrev_b32_e32 v14, 16, v9
	v_and_b32_e32 v15, 0xffff0000, v9
	v_lshlrev_b32_e32 v8, 16, v10
	v_and_b32_e32 v9, 0xffff0000, v10
	v_lshlrev_b32_e32 v10, 16, v11
	v_and_b32_e32 v11, 0xffff0000, v11
.LBB0_566:
	v_pk_add_f32 v[6:7], v[6:7], v[62:63]
	v_pk_add_f32 v[4:5], v[4:5], v[60:61]
	v_pk_add_f32 v[6:7], v[6:7], v[14:15]
	v_pk_add_f32 v[4:5], v[4:5], v[12:13]
	v_pk_add_f32 v[0:1], v[0:1], v[56:57]
	v_mul_f32_e32 v21, v21, v21
	v_pk_add_f32 v[8:9], v[0:1], v[8:9]
	v_mul_f32_e32 v0, v5, v5
	v_mul_f32_e32 v1, v7, v7
	v_fmac_f32_e32 v21, v20, v20
	v_mul_f32_e32 v20, v23, v23
	v_fmac_f32_e32 v0, v4, v4
	v_fmac_f32_e32 v1, v6, v6
	v_fmac_f32_e32 v20, v22, v22
	v_pk_add_f32 v[2:3], v[2:3], v[58:59]
	v_add_f32_e32 v0, v0, v1
	v_mul_f32_e32 v1, v9, v9
	v_add_f32_e32 v20, v21, v20
	v_mul_f32_e32 v21, v31, v31
	v_pk_add_f32 v[10:11], v[2:3], v[10:11]
	v_fmac_f32_e32 v1, v8, v8
	v_fmac_f32_e32 v21, v30, v30
	v_mul_f32_e32 v19, v19, v19
	v_add_f32_e32 v0, v1, v0
	v_mul_f32_e32 v1, v11, v11
	v_add_f32_e32 v20, v21, v20
	v_fmac_f32_e32 v19, v18, v18
	v_fmac_f32_e32 v1, v10, v10
	v_add_f32_e32 v18, v19, v20
	v_add_f32_e32 v0, v1, v0
	v_add_f32_e32 v0, v18, v0
	ds_bpermute_b32 v1, v149, v0
	v_cvt_pk_bf16_f32 v2, v4, v5
	v_cvt_pk_bf16_f32 v3, v6, v7
	v_cvt_pk_bf16_f32 v4, v8, v9
	v_cvt_pk_bf16_f32 v5, v10, v11
	s_waitcnt lgkmcnt(0)
	v_add_f32_e32 v0, v0, v1
	ds_bpermute_b32 v1, v150, v0
	global_store_dwordx4 v[16:17], v[2:5], off
	s_and_saveexec_b64 s[8:9], s[10:11]
	s_cbranch_execz .LBB0_568
	v_lshlrev_b64 v[2:3], 6, v[24:25]
	v_lshl_add_u64 v[2:3], s[40:41], 0, v[2:3]
	v_lshl_add_u64 v[2:3], s[52:53], 2, v[2:3]
	s_lshl_b32 s0, s68, 2
	v_lshl_add_u64 v[2:3], v[2:3], 0, s[0:1]
	s_waitcnt lgkmcnt(0)
	v_add_f32_e32 v0, v0, v1
	global_store_dword v[2:3], v0, off
